# mix-phase deferred 4-row transpose jobs (2 loops): load->wait->ds_write ladders turned into 4 loads in flight with counted waits
# speedup vs baseline: 1.0007x; 1.0007x over previous
; __device__ __forceinline__ unsigned pack2(float a, float b) { return (unsigned)f2bf(a) | ((unsigned)f2bf(b) << 16); }
; __device__ void transpose_job(int tid_, int bid_, int nblk_, const float* __restrict__ src, u16* __restrict__ dst, int K, int N, int nbatch,
;                               size_t sstride, size_t dstride, int ldd, float* sm) {
;     ...
;   for (int t = bid_; t < total; t += nblk_) {
;     int bi = t / per, r = t % per, kt = r / tn, nt = r % tn;
;     const float* s = src + (size_t)bi * sstride + (size_t)(kt * 32) * N + nt * 32;
; #pragma unroll
;     for (int i = 0; i < 4; ++i) {
;       int kk = (tid >> 5) + 8 * i, nn = tid & 31;
;       sm[kk * 33 + nn] = s[(size_t)kk * N + nn];
;     }
;     __syncthreads();
;     {
;       int n = tid >> 3, kc = tid & 7;
;       float v0 = sm[(kc * 4 + 0) * 33 + n], v1 = sm[(kc * 4 + 1) * 33 + n];
;       float v2 = sm[(kc * 4 + 2) * 33 + n], v3 = sm[(kc * 4 + 3) * 33 + n];
;       uint2 o;
;       o.x = pack2(v0, v1);
;       o.y = pack2(v2, v3);
;       *(uint2*)(dst + (size_t)bi * dstride + (size_t)(nt * 32 + n) * ldd + kt * 32 + kc * 4) = o;
;     }
;     __syncthreads();
; __device__ void mix_phase(int tid_, int bid_, int nblk_, const Params& p, int li, char* smem) {
;     ...
;     if (j < 100) { transpose_job(tid_, j, 100, p.od_ga_w, p.wt_gate, 160, 160, 64, 25600, 51200, 160, sm); continue; }
.LBB0_605:
	s_addk_i32 s20, 0x64
	s_and_b32 s0, s20, 0xffff
	s_mulk_i32 s0, 0x47af
	s_lshr_b32 s0, s0, 16
	s_sub_i32 s21, s20, s0
	s_bfe_u32 s21, s21, 0xf0001
	s_add_i32 s21, s21, s0
	s_lshr_b32 s0, s21, 4
	s_mul_i32 s21, s0, 25
	s_sub_i32 s21, s20, s21
	s_mul_i32 s22, s21, 0xcd
	s_lshr_b32 s23, s22, 10
	s_mul_i32 s23, s23, 5
	s_sub_i32 s21, s21, s23
	s_mul_i32 s0, s0, 0x19000
	s_add_u32 s23, s40, s0
	s_addc_u32 s24, s41, 0
	s_lshr_b32 s22, s22, 5
	s_and_b32 s25, s22, 0xe0
	s_mul_i32 s22, s25, 0x280
	s_add_u32 s22, s23, s22
	s_addc_u32 s23, s24, 0
	s_lshl_b32 s21, s21, 5
	s_and_b32 s21, s21, 0xe0
	s_lshl_b32 s24, s21, 2
	s_add_u32 s22, s22, s24
	s_addc_u32 s23, s23, 0
	v_lshlrev_b32_e32 v2, 2, v40
	v_mov_b32_e32 v3, v0
	v_lshl_add_u64 v[2:3], s[22:23], 0, v[2:3]
	v_lshl_add_u64 v[4:5], v[2:3], 0, v[44:45]
	global_load_dword v22, v[4:5], off
	v_lshl_add_u64 v[4:5], v[2:3], 0, v[46:47]
	s_add_u32 s22, s26, s0
	s_addc_u32 s23, s27, 0
	s_lshl_b32 s0, s25, 1
	v_lshlrev_b32_e32 v8, 1, v42
	v_mov_b32_e32 v9, v0
	s_cmpk_gt_u32 s20, 0x5db
	global_load_dword v23, v[4:5], off
	v_lshl_add_u64 v[4:5], v[2:3], 0, v[48:49]
	v_lshl_add_u64 v[2:3], v[2:3], 0, v[50:51]
	global_load_dword v24, v[4:5], off
	global_load_dword v25, v[2:3], off
	v_add_u32_e32 v6, v53, v157
	s_waitcnt vmcnt(3)
	ds_write_b32 v6, v22
	s_waitcnt vmcnt(2)
	ds_write_b32 v6, v23 offset:1056
	s_waitcnt vmcnt(1)
	ds_write_b32 v6, v24 offset:2112
	s_waitcnt vmcnt(0)
	ds_write_b32 v6, v25 offset:3168
	s_waitcnt lgkmcnt(0)
	s_barrier
	ds_read2_b32 v[2:3], v119 offset1:33
	ds_read2_b32 v[4:5], v119 offset0:66 offset1:99
	v_add_u32_e32 v1, s21, v55
	v_mov_b64_e32 v[6:7], s[22:23]
	v_mad_i64_i32 v[6:7], s[22:23], v1, s90, v[6:7]
	v_lshl_add_u64 v[6:7], v[6:7], 0, s[0:1]
	v_lshl_add_u64 v[6:7], v[6:7], 0, v[8:9]
	s_waitcnt lgkmcnt(0)
	v_and_b32_sdwa v1, v4, v198 dst_sel:DWORD dst_unused:UNUSED_PAD src0_sel:WORD_1 src1_sel:DWORD
	v_and_b32_sdwa v8, v2, v198 dst_sel:DWORD dst_unused:UNUSED_PAD src0_sel:WORD_1 src1_sel:DWORD
	v_add3_u32 v2, v2, v8, s63
	v_add3_u32 v1, v4, v1, s63
	v_and_b32_sdwa v4, v5, v198 dst_sel:DWORD dst_unused:UNUSED_PAD src0_sel:WORD_1 src1_sel:DWORD
	v_and_b32_sdwa v8, v3, v198 dst_sel:DWORD dst_unused:UNUSED_PAD src0_sel:WORD_1 src1_sel:DWORD
	v_add3_u32 v4, v5, v4, s63
	v_add3_u32 v3, v3, v8, s63
	v_and_b32_e32 v4, 0xffff0000, v4
	v_and_b32_e32 v5, 0xffff0000, v3
	v_or_b32_sdwa v3, v4, v1 dst_sel:DWORD dst_unused:UNUSED_PAD src0_sel:DWORD src1_sel:WORD_1
	v_or_b32_sdwa v2, v5, v2 dst_sel:DWORD dst_unused:UNUSED_PAD src0_sel:DWORD src1_sel:WORD_1
	global_store_dwordx2 v[6:7], v[2:3], off
	s_barrier
	s_cbranch_scc0 .LBB0_605
	s_mov_b64 s[20:21], 0

; __device__ __forceinline__ unsigned pack2(float a, float b) { return (unsigned)f2bf(a) | ((unsigned)f2bf(b) << 16); }
; __device__ void transpose_job(int tid_, int bid_, int nblk_, const float* __restrict__ src, u16* __restrict__ dst, int K, int N, int nbatch,
;                               size_t sstride, size_t dstride, int ldd, float* sm) {
;     ...
;   for (int t = bid_; t < total; t += nblk_) {
;     int bi = t / per, r = t % per, kt = r / tn, nt = r % tn;
;     const float* s = src + (size_t)bi * sstride + (size_t)(kt * 32) * N + nt * 32;
; #pragma unroll
;     for (int i = 0; i < 4; ++i) {
;       int kk = (tid >> 5) + 8 * i, nn = tid & 31;
;       sm[kk * 33 + nn] = s[(size_t)kk * N + nn];
;     }
;     __syncthreads();
;     {
;       int n = tid >> 3, kc = tid & 7;
;       float v0 = sm[(kc * 4 + 0) * 33 + n], v1 = sm[(kc * 4 + 1) * 33 + n];
;       float v2 = sm[(kc * 4 + 2) * 33 + n], v3 = sm[(kc * 4 + 3) * 33 + n];
;       uint2 o;
;       o.x = pack2(v0, v1);
;       o.y = pack2(v2, v3);
;       *(uint2*)(dst + (size_t)bi * dstride + (size_t)(nt * 32 + n) * ldd + kt * 32 + kc * 4) = o;
;     }
;     __syncthreads();
; __device__ void mix_phase(int tid_, int bid_, int nblk_, const Params& p, int li, char* smem) {
;     ...
;     if (j < 100) { transpose_job(tid_, j, 100, p.od_gx_w, p.wt_gate + 25600, 160, 160, 64, 25600, 51200, 160, sm); continue; }
.LBB0_610:
	s_addk_i32 s20, 0x64
	s_and_b32 s0, s20, 0xffff
	s_mulk_i32 s0, 0x47af
	s_lshr_b32 s0, s0, 16
	s_sub_i32 s21, s20, s0
	s_bfe_u32 s21, s21, 0xf0001
	s_add_i32 s21, s21, s0
	s_lshr_b32 s0, s21, 4
	s_mul_i32 s21, s0, 25
	s_sub_i32 s21, s20, s21
	s_mul_i32 s22, s21, 0xcd
	s_lshr_b32 s23, s22, 10
	s_mul_i32 s23, s23, 5
	s_sub_i32 s21, s21, s23
	s_mul_i32 s0, s0, 0x19000
	s_add_u32 s23, s36, s0
	s_addc_u32 s24, s37, 0
	s_lshr_b32 s22, s22, 5
	s_and_b32 s25, s22, 0xe0
	s_mul_i32 s22, s25, 0x280
	s_add_u32 s22, s23, s22
	s_addc_u32 s23, s24, 0
	s_lshl_b32 s21, s21, 5
	s_and_b32 s21, s21, 0xe0
	s_lshl_b32 s24, s21, 2
	s_add_u32 s22, s22, s24
	s_addc_u32 s23, s23, 0
	v_lshlrev_b32_e32 v2, 2, v40
	v_mov_b32_e32 v3, v0
	v_lshl_add_u64 v[2:3], s[22:23], 0, v[2:3]
	v_lshl_add_u64 v[4:5], v[2:3], 0, v[44:45]
	global_load_dword v22, v[4:5], off
	v_lshl_add_u64 v[4:5], v[2:3], 0, v[46:47]
	s_add_u32 s22, s10, s0
	s_addc_u32 s23, s11, 0
	s_lshl_b32 s0, s25, 1
	v_lshlrev_b32_e32 v8, 1, v42
	v_mov_b32_e32 v9, v0
	s_cmpk_gt_u32 s20, 0x5db
	global_load_dword v23, v[4:5], off
	v_lshl_add_u64 v[4:5], v[2:3], 0, v[48:49]
	v_lshl_add_u64 v[2:3], v[2:3], 0, v[50:51]
	global_load_dword v24, v[4:5], off
	global_load_dword v25, v[2:3], off
	v_add_u32_e32 v6, v53, v157
	s_waitcnt vmcnt(3)
	ds_write_b32 v6, v22
	s_waitcnt vmcnt(2)
	ds_write_b32 v6, v23 offset:1056
	s_waitcnt vmcnt(1)
	ds_write_b32 v6, v24 offset:2112
	s_waitcnt vmcnt(0)
	ds_write_b32 v6, v25 offset:3168
	s_waitcnt lgkmcnt(0)
	s_barrier
	ds_read2_b32 v[2:3], v119 offset1:33
	ds_read2_b32 v[4:5], v119 offset0:66 offset1:99
	v_add_u32_e32 v1, s21, v55
	v_mov_b64_e32 v[6:7], s[22:23]
	v_mad_i64_i32 v[6:7], s[22:23], v1, s90, v[6:7]
	v_lshl_add_u64 v[6:7], v[6:7], 0, s[0:1]
	v_lshl_add_u64 v[6:7], v[6:7], 0, v[8:9]
	s_waitcnt lgkmcnt(0)
	v_and_b32_sdwa v1, v4, v198 dst_sel:DWORD dst_unused:UNUSED_PAD src0_sel:WORD_1 src1_sel:DWORD
	v_and_b32_sdwa v8, v2, v198 dst_sel:DWORD dst_unused:UNUSED_PAD src0_sel:WORD_1 src1_sel:DWORD
	v_add3_u32 v2, v2, v8, s63
	v_add3_u32 v1, v4, v1, s63
	v_and_b32_sdwa v4, v5, v198 dst_sel:DWORD dst_unused:UNUSED_PAD src0_sel:WORD_1 src1_sel:DWORD
	v_and_b32_sdwa v8, v3, v198 dst_sel:DWORD dst_unused:UNUSED_PAD src0_sel:WORD_1 src1_sel:DWORD
	v_add3_u32 v4, v5, v4, s63
	v_add3_u32 v3, v3, v8, s63
	v_and_b32_e32 v4, 0xffff0000, v4
	v_and_b32_e32 v5, 0xffff0000, v3
	v_or_b32_sdwa v3, v4, v1 dst_sel:DWORD dst_unused:UNUSED_PAD src0_sel:DWORD src1_sel:WORD_1
	v_or_b32_sdwa v2, v5, v2 dst_sel:DWORD dst_unused:UNUSED_PAD src0_sel:DWORD src1_sel:WORD_1
	global_store_dwordx2 v[6:7], v[2:3], off
	s_barrier
	s_cbranch_scc0 .LBB0_610
	s_mov_b64 s[20:21], 0
